# bundle of small work removals on the best version: P3 peel, P5 no-rs epilogue without drain and dead rs code, incremental unit scheduling in all GEMM phases incl. fused P6
# baseline (speedup 1.0000x reference)
;     __host__ __device__ bool next(int i, Unit& u) const {
;         const long L = (long)i * G + c; if (L >= nwg) return false;
;         int wgid = (int)L; { const int q = nwg / NXCD, r = nwg % NXCD, xcd = wgid % NXCD, off = wgid / NXCD; wgid = (xcd < r ? xcd * (q + 1) : r * (q + 1) + (xcd - r) * q) + off; }
;         const int nig = WGM * nN, gid = wgid / nig, fm = gid * WGM, gsz = (nM - fm) < WGM ? (nM - fm) : WGM;
;         u.pm = fm + ((wgid % nig) % gsz); u.pn = (wgid % nig) / gsz; return true;
;     }
; template <class Epi, class Sched, bool ALIGN_EPI = false, bool SP2 = false>
; __device__ __forceinline__ void gemm_phase(PG8_LAS unsigned char* lds, const Gemm g, const Sched& S, const Epi& E) {
;     ...
;         const bool has_next = S.next(ui + 1, nxt);
;         const char* nA = has_next ? (const char*)g.A + (size_t)nxt.pm * tstep : cA; const char* nB = has_next ? (const char*)g.Bt + (size_t)nxt.pn * tstep : cB;
.LBB0_719:
	s_add_i32 s26, s26, 1
	s_cmp_lt_u32 s26, 4
	s_cselect_b64 s[6:7], -1, 0
	s_mov_b32 s36, s46
	s_add_i32 s28, s48, 8
	s_branch .LBB0_725
	s_mov_b32 s27, s15
	s_lshl_b64 s[6:7], s[26:27], 8
	s_add_u32 s42, s6, s2
	s_addc_u32 s43, s7, s19
	v_cmp_gt_i64_e32 vcc, s[42:43], v[204:205]
	v_cmp_lt_i64_e64 s[6:7], s[42:43], v[202:203]
	s_cbranch_vccnz .LBB0_725
	s_ashr_i32 s27, s42, 31
	s_lshr_b32 s27, s27, 29
	s_add_i32 s27, s42, s27
	s_and_b32 s28, s27, -8
	s_sub_i32 s36, s42, s28
	s_cmp_gt_i32 s36, -1
	s_mov_b64 s[28:29], -1
	s_cbranch_scc0 .LBB0_722
	s_lshl_b32 s37, s36, 7
	s_mov_b64 s[28:29], 0
